# wave remap: softmax map c = wave>>2, row block j = (wave&3)^(2c) so each SIMD hosts one map-0 wave in the unit epilogue
# speedup vs baseline: 1.0784x; 1.0035x over previous
.LBB0_517:
	s_or_b64 exec, exec, s[0:1]
	s_add_i32 s62, 0, 0x22820
	v_mov_b32_e32 v8, s62
	s_waitcnt lgkmcnt(0)
	s_barrier
	ds_read_b32 v8, v8
	s_movk_i32 s0, 0x7ff
	s_mov_b32 s9, 0
	s_waitcnt lgkmcnt(0)
	s_barrier
	v_cmp_lt_i32_e32 vcc, s0, v8
	v_readfirstlane_b32 s60, v8
	s_cbranch_vccnz .LBB0_565
	v_add_f32_e32 v6, v6, v7
	s_mov_b32 s0, 0x3fb8aa3b
	v_mul_f32_e32 v7, 0x3fb8aa3b, v6
	v_fma_f32 v8, v6, s0, -v7
	v_rndne_f32_e32 v9, v7
	v_fmac_f32_e32 v8, 0x32a5705f, v6
	v_sub_f32_e32 v7, v7, v9
	v_add_f32_e32 v7, v7, v8
	v_exp_f32_e32 v7, v7
	v_cvt_i32_f32_e32 v8, v9
	v_add_f32_e32 v4, v4, v5
	s_mov_b32 s1, 0xc2ce8ed0
	v_cmp_ngt_f32_e32 vcc, s1, v6
	v_ldexp_f32 v5, v7, v8
	v_mul_f32_e32 v7, 0x3fb8aa3b, v4
	v_fma_f32 v8, v4, s0, -v7
	v_rndne_f32_e32 v9, v7
	v_fmac_f32_e32 v8, 0x32a5705f, v4
	v_sub_f32_e32 v7, v7, v9
	v_add_f32_e32 v7, v7, v8
	v_exp_f32_e32 v7, v7
	v_cvt_i32_f32_e32 v8, v9
	s_mov_b32 s4, 0x42b17218
	v_cndmask_b32_e32 v5, 0, v5, vcc
	v_mov_b32_e32 v9, 0x7f800000
	v_cmp_nlt_f32_e32 vcc, s4, v6
	v_ldexp_f32 v6, v7, v8
	s_waitcnt vmcnt(0)
	v_add_f32_e32 v3, v3, v3
	v_cndmask_b32_e32 v5, v9, v5, vcc
	v_cmp_ngt_f32_e32 vcc, s1, v4
	s_mov_b32 s71, 0xf800000
	s_add_u32 s63, s50, 0x8000000
	v_cndmask_b32_e32 v6, 0, v6, vcc
	v_cmp_nlt_f32_e32 vcc, s4, v4
	s_addc_u32 s64, s51, 0
	s_add_u32 s65, s50, 0xc000000
	v_cndmask_b32_e32 v4, v9, v6, vcc
	v_sub_f32_e32 v4, v5, v4
	v_mul_f32_e32 v5, 0x4f800000, v3
	v_cmp_gt_f32_e32 vcc, s71, v3
	v_lshlrev_b32_e32 v6, 3, v1
	v_add_f32_e32 v169, 0x3e4ccccd, v4
	v_cndmask_b32_e32 v3, v3, v5, vcc
	v_sqrt_f32_e32 v5, v3
	v_lshlrev_b32_e32 v4, 1, v1
	v_and_b32_e32 v6, 24, v6
	v_and_or_b32 v9, v4, 32, v6
	v_add_u32_e32 v4, -1, v5
	v_fma_f32 v6, -v4, v5, v3
	v_cmp_ge_f32_e64 s[0:1], 0, v6
	v_add_u32_e32 v6, 1, v5
	s_addc_u32 s70, s51, 0
	v_cndmask_b32_e64 v4, v5, v4, s[0:1]
	v_fma_f32 v5, -v6, v5, v3
	v_cmp_lt_f32_e64 s[0:1], 0, v5
	s_lshr_b32 s4, s10, 6
	s_bfe_u32 s5, s10, 0x10008
	v_cndmask_b32_e64 v4, v4, v6, s[0:1]
	v_lshrrev_b32_e32 v199, 4, v1
	v_mul_f32_e32 v5, 0x37800000, v4
	s_lshl_b32 s4, s4, 2
	v_cndmask_b32_e32 v4, v4, v5, vcc
	v_mov_b32_e32 v5, s67
	s_add_i32 s67, s4, 0
	s_movk_i32 s4, 0x110
	v_add_u32_e32 v10, 32, v199
	s_lshl_b32 s12, s5, 7
	v_mad_u32_u24 v202, v199, s4, 0
	v_mul_u32_u24_e32 v11, 48, v10
	s_movk_i32 s11, 0x2200
	s_add_i32 s12, s12, 0
	v_or_b32_e32 v7, v166, v174
	v_mov_b32_e32 v200, 0x260
	v_lshlrev_b32_e32 v6, 3, v2
	v_mad_u32_u24 v204, v199, 48, v202
	v_add3_u32 v12, v202, v11, s11
	s_movk_i32 s11, 0x140
	v_lshlrev_b32_e32 v205, 4, v2
	v_mov_b32_e32 v2, s12
	s_bfe_u32 s8, s10, 0x20006
	s_lshl_b32 s98, s5, 1
	s_xor_b32 s8, s8, s98
	v_cmp_class_f32_e32 vcc, v3, v200
	v_mul_i32_i24_e32 v7, 0x140, v7
	v_mad_u32_u24 v206, v178, s4, v2
	v_add_u32_e32 v208, 0x2800, v204
	v_mad_u32_u24 v209, v199, s11, 0
	s_movk_i32 s4, 0xffd0
	v_cndmask_b32_e32 v3, v4, v3, vcc
	v_add3_u32 v207, 0, v9, v7
	v_mad_i32_i24 v2, v10, s4, v208
	v_mad_i32_i24 v7, v199, s4, v209
	s_lshl_b32 s4, s8, 14
	v_mul_f32_e32 v201, 0x3f828f5c, v3
	v_mov_b32_e32 v3, 0
	s_add_i32 s4, s4, 0
	v_mov_b32_e32 v4, s66
	s_lshl_b32 s66, s8, 5
	s_lshl_b32 s14, s5, 6
	v_lshlrev_b32_e32 v8, 3, v167
	s_add_i32 s67, s67, 0x22800
	v_lshlrev_b32_e32 v203, 4, v167
	s_add_i32 s4, s4, 0x12800
	s_and_b32 s8, 0x100, s10
	v_mov_b32_e32 v167, v3
	s_cmp_eq_u32 s5, 0
	v_lshl_add_u64 v[170:171], v[166:167], 2, v[4:5]
	v_lshlrev_b64 v[4:5], 1, v[166:167]
	s_cselect_b64 s[10:11], -1, 0
	s_cmp_lg_u32 s8, 0
	v_lshl_add_u32 v211, v142, 2, s4
	v_lshl_add_u64 v[10:11], s[50:51], 0, v[4:5]
	s_mov_b64 s[4:5], 0x10000000
	v_lshl_add_u64 v[176:177], s[42:43], 0, v[4:5]
	v_sub_u32_e32 v4, v166, v178
	s_mov_b32 s16, 2.0
	s_mov_b32 s18, 0x41000000
	s_mov_b32 s20, 0x41200000
	s_mov_b32 s22, 0x41800000
	s_mov_b32 s24, 0x41900000
	s_mov_b32 s36, 0x41c00000
	s_mov_b32 s54, 0x41d00000
	v_or_b32_e32 v198, 0x780, v178
	v_cmp_eq_u32_e64 s[0:1], 0, v142
	v_add_u32_e32 v210, 0xd800, v207
	s_cselect_b64 s[12:13], -1, 0
	v_mov_b32_e32 v172, v169
	v_mov_b32_e32 v173, v169
	v_lshl_add_u64 v[174:175], v[10:11], 0, s[4:5]
	v_subrev_u32_e32 v167, s66, v4
	s_lshl_b32 s14, s14, 1
	s_mov_b32 s15, s9
	v_lshlrev_b32_e32 v178, 1, v6
	s_mov_b32 s72, 0x42fc0000
	v_lshlrev_b32_e32 v180, 1, v8
	s_mov_b32 s73, 0x10000
	s_mov_b32 s17, 0x40400000
	s_add_i32 s74, 0, 0x22810
	s_mov_b32 s75, 0x425c0000
	s_mov_b32 s19, 0x41100000
	s_mov_b32 s21, 0x41300000
	s_mov_b32 s23, 0x41880000
	s_mov_b32 s25, 0x41980000
	s_mov_b32 s37, 0x41c80000
	s_mov_b32 s55, 0x41d80000
	v_add_u32_e32 v212, v7, v203
	v_add_u32_e32 v213, v2, v203
	v_mov_b32_e32 v214, 0x3727c5ac
	s_mov_b32 s76, 0x3f4ccccd
	s_movk_i32 s77, 0x800
	v_mov_b32_e32 v215, 0x42800000
	v_add_u32_e32 v216, v12, v203
	v_mov_b32_e32 v217, 0xff800000
	s_branch .LBB0_520
